# top-16 radix select: 4 chains in flight per half step with scalar count test; P4/P5 work queues: only wave 0 of a workgroup probes other XCD queues
# speedup vs baseline: 1.0210x; 1.0077x over previous
.LBB0_551:
	s_lshl_b32 s5, 1, s4
	s_or_b32 s7, s5, s6
	v_cmp_le_u32_e64 vcc, s7, v7
	s_or_b32 s50, s5, s3
	v_cmp_le_u32_e64 s[44:45], s50, v6
	s_or_b32 s7, s5, s33
	v_cmp_le_u32_e64 s[98:99], s7, v5
	s_or_b32 s50, s5, s38
	v_cmp_le_u32_e64 s[100:101], s50, v4
	s_bcnt1_i32_b64 s50, vcc
	s_cmp_gt_u32 s50, 15
	s_cselect_b32 s50, s5, 0
	s_or_b32 s6, s6, s50
	s_bcnt1_i32_b64 s50, s[44:45]
	s_cmp_gt_u32 s50, 15
	s_cselect_b32 s50, s5, 0
	s_or_b32 s3, s3, s50
	s_bcnt1_i32_b64 s50, s[98:99]
	s_cmp_gt_u32 s50, 15
	s_cselect_b32 s50, s5, 0
	s_or_b32 s33, s33, s50
	s_bcnt1_i32_b64 s50, s[100:101]
	s_cmp_gt_u32 s50, 15
	s_cselect_b32 s50, s5, 0
	s_or_b32 s38, s38, s50
	s_or_b32 s7, s5, s27
	v_cmp_le_u32_e64 vcc, s7, v2
	s_or_b32 s50, s5, s26
	v_cmp_le_u32_e64 s[44:45], s50, v0
	s_or_b32 s7, s5, s24
	v_cmp_le_u32_e64 s[98:99], s7, v3
	s_or_b32 s50, s5, s23
	v_cmp_le_u32_e64 s[100:101], s50, v1
	s_bcnt1_i32_b64 s50, vcc
	s_cmp_gt_u32 s50, 15
	s_cselect_b32 s50, s5, 0
	s_or_b32 s27, s27, s50
	s_bcnt1_i32_b64 s50, s[44:45]
	s_cmp_gt_u32 s50, 15
	s_cselect_b32 s50, s5, 0
	s_or_b32 s26, s26, s50
	s_bcnt1_i32_b64 s50, s[98:99]
	s_cmp_gt_u32 s50, 15
	s_cselect_b32 s50, s5, 0
	s_or_b32 s24, s24, s50
	s_bcnt1_i32_b64 s50, s[100:101]
	s_cmp_gt_u32 s50, 15
	s_cselect_b32 s50, s5, 0
	s_or_b32 s23, s23, s50
	s_add_i32 s4, s4, -1
	s_cmp_eq_u32 s4, -1
	s_cbranch_scc0 .LBB0_551
	v_cmp_lt_u32_e64 s[4:5], s6, v7
	s_bcnt1_i32_b64 s50, s[4:5]
	v_cmp_lt_u64_e64 s[44:45], s[50:51], 16
	v_cmp_eq_u32_e64 s[6:7], s6, v7
	s_and_b64 vcc, exec, s[44:45]
	s_cbranch_vccz .LBB0_555
	s_sub_i32 s10, 17, s50

.LBB0_665:
	v_readfirstlane_b32 s98, v210
	s_cmp_lg_u32 s98, 0
	s_cbranch_scc1 .LBB0_706
	s_add_i32 s20, s20, 1
	s_add_i32 s18, s18, 1
	s_xor_b64 s[0:1], s[0:1], -1
	s_cmp_eq_u32 s20, 8
	s_cbranch_scc1 .LBB0_706
